# static priority for waves 4-7 in the out-projection K-loop too (the earlier change was the V-transpose GEMM loop): per-block s_setprio flips removed, one raise before the loop, reset after
# speedup vs baseline: 1.0021x; 1.0021x over previous
; template <class Epi, class Sched, bool ALIGN_EPI, bool SP2>
; __device__ __forceinline__ void gemm_phase(LAS unsigned char* lds, const Gemm g, const Sched& S, const Epi& E, int tid_in) {
;     ...
; #pragma unroll
;         for (int a = 0; a < 2; ++a)
; #pragma unroll
;             for (int b = 0; b < 2; ++b)
; #pragma unroll
;                 for (int m = 0; m < 4; ++m)
; #pragma unroll
;                     for (int n = 0; n < 2; ++n) acc[a][b][m][n] = (f32x4){0.f, 0.f, 0.f, 0.f};
;         cur = nxt; cA = nA; cB = nB; ++ui;
.LBB0_51:
	s_lshl_b32 s71, s61, 21
	s_and_b64 s[4:5], s[36:37], exec
	s_cselect_b32 s4, s71, s30
	s_lshl_b32 s70, s60, 21
	v_mov_b32_e32 v2, v1
	v_mov_b32_e32 v3, v1
	s_and_b64 s[14:15], s[36:37], exec
	v_mov_b32_e32 v0, v1
	v_mov_b64_e32 v[6:7], v[2:3]
	s_waitcnt vmcnt(19)
	v_mov_b64_e32 v[10:11], v[2:3]
	s_waitcnt vmcnt(16)
	v_mov_b64_e32 v[22:23], v[2:3]
	s_waitcnt vmcnt(15)
	v_mov_b64_e32 v[26:27], v[2:3]
	s_waitcnt vmcnt(14)
	v_mov_b64_e32 v[38:39], v[2:3]
	v_mov_b64_e32 v[42:43], v[2:3]
	v_mov_b64_e32 v[54:55], v[2:3]
	v_mov_b64_e32 v[58:59], v[2:3]
	v_mov_b64_e32 v[14:15], v[2:3]
	v_mov_b64_e32 v[18:19], v[2:3]
	v_mov_b64_e32 v[30:31], v[2:3]
	v_mov_b64_e32 v[34:35], v[2:3]
	v_mov_b64_e32 v[46:47], v[2:3]
	v_mov_b64_e32 v[50:51], v[2:3]
	v_mov_b64_e32 v[62:63], v[2:3]
	v_mov_b64_e32 v[66:67], v[2:3]
	v_mov_b64_e32 v[70:71], v[2:3]
	v_mov_b64_e32 v[74:75], v[2:3]
	v_mov_b64_e32 v[86:87], v[2:3]
	v_mov_b64_e32 v[90:91], v[2:3]
	v_mov_b64_e32 v[102:103], v[2:3]
	v_mov_b64_e32 v[106:107], v[2:3]
	v_mov_b64_e32 v[122:123], v[2:3]
	v_mov_b64_e32 v[126:127], v[2:3]
	v_mov_b64_e32 v[78:79], v[2:3]
	v_mov_b64_e32 v[82:83], v[2:3]
	v_mov_b64_e32 v[94:95], v[2:3]
	v_mov_b64_e32 v[98:99], v[2:3]
	v_mov_b64_e32 v[110:111], v[2:3]
	v_mov_b64_e32 v[118:119], v[2:3]
	v_mov_b64_e32 v[134:135], v[2:3]
	v_mov_b64_e32 v[138:139], v[2:3]
	s_cselect_b32 s5, s70, s31
	s_addk_i32 s31, 0x100
	s_mov_b32 s65, -2
	s_mov_b32 s66, 0
	v_mov_b64_e32 v[4:5], v[0:1]
	v_mov_b64_e32 v[8:9], v[0:1]
	v_mov_b64_e32 v[20:21], v[0:1]
	v_mov_b64_e32 v[24:25], v[0:1]
	v_mov_b64_e32 v[36:37], v[0:1]
	v_mov_b64_e32 v[40:41], v[0:1]
	v_mov_b64_e32 v[52:53], v[0:1]
	v_mov_b64_e32 v[56:57], v[0:1]
	v_mov_b64_e32 v[12:13], v[0:1]
	v_mov_b64_e32 v[16:17], v[0:1]
	v_mov_b64_e32 v[28:29], v[0:1]
	v_mov_b64_e32 v[32:33], v[0:1]
	v_mov_b64_e32 v[44:45], v[0:1]
	v_mov_b64_e32 v[48:49], v[0:1]
	v_mov_b64_e32 v[60:61], v[0:1]
	v_mov_b64_e32 v[64:65], v[0:1]
	v_mov_b64_e32 v[68:69], v[0:1]
	v_mov_b64_e32 v[72:73], v[0:1]
	v_mov_b64_e32 v[84:85], v[0:1]
	v_mov_b64_e32 v[88:89], v[0:1]
	v_mov_b64_e32 v[100:101], v[0:1]
	v_mov_b64_e32 v[104:105], v[0:1]
	v_mov_b64_e32 v[120:121], v[0:1]
	v_mov_b64_e32 v[124:125], v[0:1]
	v_mov_b64_e32 v[76:77], v[0:1]
	v_mov_b64_e32 v[80:81], v[0:1]
	v_mov_b64_e32 v[92:93], v[0:1]
	v_mov_b64_e32 v[96:97], v[0:1]
	v_mov_b64_e32 v[108:109], v[0:1]
	v_mov_b64_e32 v[116:117], v[0:1]
	v_mov_b64_e32 v[132:133], v[0:1]
	v_mov_b64_e32 v[136:137], v[0:1]
	s_and_b64 vcc, exec, s[46:47]
	s_cbranch_vccnz .Lpr_skip52
	s_setprio 1

; #define PG8_STAGE(bufoff, goff, voff) do { _Pragma("unroll") for (int _i = 0; _i < 2; ++_i) \
;         __builtin_amdgcn_raw_ptr_buffer_load_lds(R_##voff, (LAS void*)(lds + (bufoff) + ldsw + _i * 8192), 16, (int)(voff)[_i], (int)(goff), 0, 0); } while (0)
; #define PG8_WAIT_V(n) asm volatile("s_waitcnt vmcnt(" #n ")" ::: "memory")
; #define PG8_WAIT_L(n) asm volatile("s_waitcnt lgkmcnt(" #n ")" ::: "memory")
; #define PG8_BAR __builtin_amdgcn_s_barrier()
; #define PG8_SCHED __builtin_amdgcn_sched_barrier(0)
; template <class Epi, class Sched, bool ALIGN_EPI, bool SP2>
; __device__ __forceinline__ void gemm_phase(LAS unsigned char* lds, const Gemm g, const Sched& S, const Epi& E, int tid_in) {
;     ...
;             PG8_LDB(B0, 0, 0); PG8_LDB(B1, 0, 1); PG8_SCHED; PG8_LDA(At, 0, 0); PG8_STAGE(PG8_SA(1, 1), a1 + hstepA, voffA);
;             PG8_WAIT_V(8); PG8_WAIT_L(0); PG8_BAR; PG8_MMA(0, 0, At, B0); PG8_MMA(0, 1, At, B1); PG8_BAR; PG8_SCHED;
;             PG8_LDA(At, 0, 1); PG8_STAGE(PG8_SB(0, 0), b2, voffB); PG8_STAGE(PG8_SB(0, 1), b2 + hstepB, voffB); PG8_STAGE(PG8_SA(0, 0), a2, voffA);
;             PG8_WAIT_V(8); PG8_WAIT_L(0); PG8_BAR; PG8_MMA(1, 0, At, B0); PG8_MMA(1, 1, At, B1); PG8_BAR; PG8_SCHED;
.LBB0_52:
	v_add_u32_e32 v0, 0x10000, v238
	ds_read_b128 v[128:131], v0
	ds_read_b128 v[140:143], v0 offset:1024
	ds_read_b128 v[144:147], v0 offset:2048
	ds_read_b128 v[148:151], v0 offset:3072
	v_add_u32_e32 v0, 0x14000, v238
	ds_read_b128 v[152:155], v0
	ds_read_b128 v[156:159], v0 offset:1024
	ds_read_b128 v[160:163], v0 offset:2048
	ds_read_b128 v[164:167], v0 offset:3072
	s_add_i32 s14, s30, s66
	s_add_i32 s15, s14, 0x100
	s_add_i32 s42, s31, s66
	s_cmpk_eq_i32 s66, 0x1f00
	s_cselect_b32 s15, s4, s15
	s_cselect_b32 s68, s5, s42
	s_or_b32 s67, s15, 0x80
	s_or_b32 s69, s68, 0x80
	s_add_i32 s14, s14, 0x100080
	s_mov_b32 m0, s54
	ds_read_b128 v[168:171], v239
	ds_read_b128 v[172:175], v239 offset:1024
	ds_read_b128 v[176:179], v239 offset:2048
	ds_read_b128 v[180:183], v239 offset:3072
	ds_read_b128 v[184:187], v239 offset:4096
	ds_read_b128 v[188:191], v239 offset:5120
	ds_read_b128 v[192:195], v239 offset:6144
	ds_read_b128 v[196:199], v239 offset:7168
	buffer_load_dwordx4 v115, s[84:87], s14 offen lds
	s_mov_b32 m0, s56
	s_nop 0
	buffer_load_dwordx4 v229, s[84:87], s14 offen lds
	s_waitcnt vmcnt(8)
	s_waitcnt lgkmcnt(0)
	s_barrier
	s_waitcnt lgkmcnt(7)
	v_mfma_f32_16x16x32_bf16 v[136:139], v[128:131], v[168:171], v[136:139]
	v_mfma_f32_16x16x32_bf16 v[132:135], v[144:147], v[168:171], v[132:135]
	s_waitcnt lgkmcnt(5)
	v_mfma_f32_16x16x32_bf16 v[116:119], v[128:131], v[176:179], v[116:119]
	v_mfma_f32_16x16x32_bf16 v[108:111], v[144:147], v[176:179], v[108:111]
	s_waitcnt lgkmcnt(3)
	v_mfma_f32_16x16x32_bf16 v[96:99], v[128:131], v[184:187], v[96:99]
	v_mfma_f32_16x16x32_bf16 v[92:95], v[144:147], v[184:187], v[92:95]
	s_waitcnt lgkmcnt(1)
	v_mfma_f32_16x16x32_bf16 v[80:83], v[128:131], v[192:195], v[80:83]
	v_mfma_f32_16x16x32_bf16 v[76:79], v[144:147], v[192:195], v[76:79]
	v_mfma_f32_16x16x32_bf16 v[136:139], v[140:143], v[172:175], v[136:139]
	v_mfma_f32_16x16x32_bf16 v[132:135], v[148:151], v[172:175], v[132:135]
	v_mfma_f32_16x16x32_bf16 v[116:119], v[140:143], v[180:183], v[116:119]
	v_mfma_f32_16x16x32_bf16 v[108:111], v[148:151], v[180:183], v[108:111]
	v_mfma_f32_16x16x32_bf16 v[96:99], v[140:143], v[188:191], v[96:99]
	v_mfma_f32_16x16x32_bf16 v[92:95], v[148:151], v[188:191], v[92:95]
	s_waitcnt lgkmcnt(0)
	v_mfma_f32_16x16x32_bf16 v[80:83], v[140:143], v[196:199], v[80:83]
	v_mfma_f32_16x16x32_bf16 v[76:79], v[148:151], v[196:199], v[76:79]
	v_mfma_f32_16x16x32_bf16 v[124:127], v[152:155], v[168:171], v[124:127]
	v_mfma_f32_16x16x32_bf16 v[120:123], v[160:163], v[168:171], v[120:123]
	v_mfma_f32_16x16x32_bf16 v[104:107], v[152:155], v[176:179], v[104:107]
	v_mfma_f32_16x16x32_bf16 v[100:103], v[160:163], v[176:179], v[100:103]
	v_mfma_f32_16x16x32_bf16 v[88:91], v[152:155], v[184:187], v[88:91]
	v_mfma_f32_16x16x32_bf16 v[84:87], v[160:163], v[184:187], v[84:87]
	v_mfma_f32_16x16x32_bf16 v[72:75], v[152:155], v[192:195], v[72:75]
	v_mfma_f32_16x16x32_bf16 v[68:71], v[160:163], v[192:195], v[68:71]
	v_mfma_f32_16x16x32_bf16 v[124:127], v[156:159], v[172:175], v[124:127]
	v_mfma_f32_16x16x32_bf16 v[120:123], v[164:167], v[172:175], v[120:123]
	v_mfma_f32_16x16x32_bf16 v[104:107], v[156:159], v[180:183], v[104:107]
	v_mfma_f32_16x16x32_bf16 v[100:103], v[164:167], v[180:183], v[100:103]
	v_mfma_f32_16x16x32_bf16 v[88:91], v[156:159], v[188:191], v[88:91]
	v_mfma_f32_16x16x32_bf16 v[84:87], v[164:167], v[188:191], v[84:87]
	v_mfma_f32_16x16x32_bf16 v[72:75], v[156:159], v[196:199], v[72:75]
	v_mfma_f32_16x16x32_bf16 v[68:71], v[164:167], v[196:199], v[68:71]
	s_barrier
	s_mov_b32 m0, s7
	s_mov_b32 s42, s86
	s_mov_b32 s43, s87
	ds_read_b128 v[168:171], v239 offset:16384
	ds_read_b128 v[172:175], v239 offset:17408
	ds_read_b128 v[176:179], v239 offset:18432
	ds_read_b128 v[180:183], v239 offset:19456
	ds_read_b128 v[184:187], v239 offset:20480
	ds_read_b128 v[188:191], v239 offset:21504
	ds_read_b128 v[192:195], v239 offset:22528
	ds_read_b128 v[196:199], v239 offset:23552
	buffer_load_dwordx4 v228, s[40:43], s68 offen lds
	s_mov_b32 m0, s9
	s_add_i32 s14, s68, 0x40000
	buffer_load_dwordx4 v230, s[40:43], s68 offen lds
	s_mov_b32 m0, s10
	s_nop 0
	buffer_load_dwordx4 v228, s[40:43], s14 offen lds
	s_mov_b32 m0, s12
	s_nop 0
	buffer_load_dwordx4 v230, s[40:43], s14 offen lds
	s_mov_b32 m0, s6
	s_nop 0
	buffer_load_dwordx4 v115, s[84:87], s15 offen lds
	s_mov_b32 m0, s13
	s_nop 0
	buffer_load_dwordx4 v229, s[84:87], s15 offen lds
	s_waitcnt vmcnt(8)
	s_waitcnt lgkmcnt(0)
	s_barrier
	s_waitcnt lgkmcnt(7)
	v_mfma_f32_16x16x32_bf16 v[64:67], v[128:131], v[168:171], v[64:67]
	v_mfma_f32_16x16x32_bf16 v[60:63], v[144:147], v[168:171], v[60:63]
	s_waitcnt lgkmcnt(5)
	v_mfma_f32_16x16x32_bf16 v[48:51], v[128:131], v[176:179], v[48:51]
	v_mfma_f32_16x16x32_bf16 v[44:47], v[144:147], v[176:179], v[44:47]
	s_waitcnt lgkmcnt(3)
	v_mfma_f32_16x16x32_bf16 v[32:35], v[128:131], v[184:187], v[32:35]
	v_mfma_f32_16x16x32_bf16 v[28:31], v[144:147], v[184:187], v[28:31]
	s_waitcnt lgkmcnt(1)
	v_mfma_f32_16x16x32_bf16 v[16:19], v[128:131], v[192:195], v[16:19]
	v_mfma_f32_16x16x32_bf16 v[12:15], v[144:147], v[192:195], v[12:15]
	v_mfma_f32_16x16x32_bf16 v[64:67], v[140:143], v[172:175], v[64:67]
	v_mfma_f32_16x16x32_bf16 v[60:63], v[148:151], v[172:175], v[60:63]
	v_mfma_f32_16x16x32_bf16 v[48:51], v[140:143], v[180:183], v[48:51]
	v_mfma_f32_16x16x32_bf16 v[44:47], v[148:151], v[180:183], v[44:47]
	v_mfma_f32_16x16x32_bf16 v[32:35], v[140:143], v[188:191], v[32:35]
	v_mfma_f32_16x16x32_bf16 v[28:31], v[148:151], v[188:191], v[28:31]
	s_waitcnt lgkmcnt(0)
	v_mfma_f32_16x16x32_bf16 v[16:19], v[140:143], v[196:199], v[16:19]
	v_mfma_f32_16x16x32_bf16 v[12:15], v[148:151], v[196:199], v[12:15]
	v_mfma_f32_16x16x32_bf16 v[56:59], v[152:155], v[168:171], v[56:59]
	v_mfma_f32_16x16x32_bf16 v[52:55], v[160:163], v[168:171], v[52:55]
	v_mfma_f32_16x16x32_bf16 v[40:43], v[152:155], v[176:179], v[40:43]
	v_mfma_f32_16x16x32_bf16 v[36:39], v[160:163], v[176:179], v[36:39]
	v_mfma_f32_16x16x32_bf16 v[24:27], v[152:155], v[184:187], v[24:27]
	v_mfma_f32_16x16x32_bf16 v[20:23], v[160:163], v[184:187], v[20:23]
	v_mfma_f32_16x16x32_bf16 v[8:11], v[152:155], v[192:195], v[8:11]
	v_mfma_f32_16x16x32_bf16 v[2:5], v[160:163], v[192:195], v[4:7]
	v_mfma_f32_16x16x32_bf16 v[56:59], v[156:159], v[172:175], v[56:59]
	v_mfma_f32_16x16x32_bf16 v[52:55], v[164:167], v[172:175], v[52:55]
	v_mfma_f32_16x16x32_bf16 v[40:43], v[156:159], v[180:183], v[40:43]
	v_mfma_f32_16x16x32_bf16 v[36:39], v[164:167], v[180:183], v[36:39]
	v_mfma_f32_16x16x32_bf16 v[24:27], v[156:159], v[188:191], v[24:27]
	v_mfma_f32_16x16x32_bf16 v[20:23], v[164:167], v[188:191], v[20:23]
	v_mfma_f32_16x16x32_bf16 v[8:11], v[156:159], v[196:199], v[8:11]
	v_mfma_f32_16x16x32_bf16 v[2:5], v[164:167], v[196:199], v[2:5]
	s_barrier
; #define PG8_STAGE(bufoff, goff, voff) do { _Pragma("unroll") for (int _i = 0; _i < 2; ++_i) \
;         __builtin_amdgcn_raw_ptr_buffer_load_lds(R_##voff, (LAS void*)(lds + (bufoff) + ldsw + _i * 8192), 16, (int)(voff)[_i], (int)(goff), 0, 0); } while (0)
; #define PG8_WAIT_V(n) asm volatile("s_waitcnt vmcnt(" #n ")" ::: "memory")
; #define PG8_WAIT_L(n) asm volatile("s_waitcnt lgkmcnt(" #n ")" ::: "memory")
; #define PG8_BAR __builtin_amdgcn_s_barrier()
; #define PG8_SCHED __builtin_amdgcn_sched_barrier(0)
; template <class Epi, class Sched, bool ALIGN_EPI, bool SP2>
; __device__ __forceinline__ void gemm_phase(LAS unsigned char* lds, const Gemm g, const Sched& S, const Epi& E, int tid_in) {
;     ...
;             PG8_LDB(B0, 1, 0); PG8_LDB(B1, 1, 1); PG8_SCHED; PG8_LDA(At, 1, 0); PG8_STAGE(PG8_SA(0, 1), a2 + hstepA, voffA);
;             PG8_WAIT_V(8); PG8_WAIT_L(0); PG8_BAR; PG8_MMA(0, 0, At, B0); PG8_MMA(0, 1, At, B1); PG8_BAR; PG8_SCHED;
;             PG8_LDA(At, 1, 1); PG8_STAGE(PG8_SB(1, 0), b3, voffB); PG8_STAGE(PG8_SB(1, 1), b3 + hstepB, voffB); PG8_STAGE(PG8_SA(1, 0), a3, voffA);
;             PG8_WAIT_V(8); PG8_WAIT_L(0); PG8_BAR; PG8_MMA(1, 0, At, B0); PG8_MMA(1, 1, At, B1); PG8_BAR; PG8_SCHED;
	v_add_u32_e32 v0, 0x18000, v238
	ds_read_b128 v[128:131], v0
	ds_read_b128 v[140:143], v0 offset:1024
	ds_read_b128 v[144:147], v0 offset:2048
	ds_read_b128 v[148:151], v0 offset:3072
	v_add_u32_e32 v0, 0x1c000, v238
	ds_read_b128 v[152:155], v0
	ds_read_b128 v[156:159], v0 offset:1024
	ds_read_b128 v[160:163], v0 offset:2048
	ds_read_b128 v[164:167], v0 offset:3072
	s_add_i32 s15, s15, 0x100000
	s_mov_b32 m0, s16
	ds_read_b128 v[168:171], v239 offset:32768
	ds_read_b128 v[172:175], v239 offset:33792
	ds_read_b128 v[176:179], v239 offset:34816
	ds_read_b128 v[180:183], v239 offset:35840
	ds_read_b128 v[184:187], v239 offset:36864
	ds_read_b128 v[188:191], v239 offset:37888
	ds_read_b128 v[192:195], v239 offset:38912
	ds_read_b128 v[196:199], v239 offset:39936
	buffer_load_dwordx4 v115, s[84:87], s15 offen lds
	s_mov_b32 m0, s17
	s_nop 0
	buffer_load_dwordx4 v229, s[84:87], s15 offen lds
	s_waitcnt vmcnt(8)
	s_waitcnt lgkmcnt(0)
	s_barrier
	s_waitcnt lgkmcnt(7)
	v_mfma_f32_16x16x32_bf16 v[136:139], v[128:131], v[168:171], v[136:139]
	v_mfma_f32_16x16x32_bf16 v[132:135], v[144:147], v[168:171], v[132:135]
	s_waitcnt lgkmcnt(5)
	v_mfma_f32_16x16x32_bf16 v[116:119], v[128:131], v[176:179], v[116:119]
	v_mfma_f32_16x16x32_bf16 v[108:111], v[144:147], v[176:179], v[108:111]
	s_waitcnt lgkmcnt(3)
	v_mfma_f32_16x16x32_bf16 v[96:99], v[128:131], v[184:187], v[96:99]
	v_mfma_f32_16x16x32_bf16 v[92:95], v[144:147], v[184:187], v[92:95]
	s_waitcnt lgkmcnt(1)
	v_mfma_f32_16x16x32_bf16 v[80:83], v[128:131], v[192:195], v[80:83]
	v_mfma_f32_16x16x32_bf16 v[76:79], v[144:147], v[192:195], v[76:79]
	v_mfma_f32_16x16x32_bf16 v[136:139], v[140:143], v[172:175], v[136:139]
	v_mfma_f32_16x16x32_bf16 v[132:135], v[148:151], v[172:175], v[132:135]
	v_mfma_f32_16x16x32_bf16 v[116:119], v[140:143], v[180:183], v[116:119]
	v_mfma_f32_16x16x32_bf16 v[108:111], v[148:151], v[180:183], v[108:111]
	v_mfma_f32_16x16x32_bf16 v[96:99], v[140:143], v[188:191], v[96:99]
	v_mfma_f32_16x16x32_bf16 v[92:95], v[148:151], v[188:191], v[92:95]
	s_waitcnt lgkmcnt(0)
	v_mfma_f32_16x16x32_bf16 v[80:83], v[140:143], v[196:199], v[80:83]
	v_mfma_f32_16x16x32_bf16 v[76:79], v[148:151], v[196:199], v[76:79]
	v_mfma_f32_16x16x32_bf16 v[124:127], v[152:155], v[168:171], v[124:127]
	v_mfma_f32_16x16x32_bf16 v[120:123], v[160:163], v[168:171], v[120:123]
	v_mfma_f32_16x16x32_bf16 v[104:107], v[152:155], v[176:179], v[104:107]
	v_mfma_f32_16x16x32_bf16 v[100:103], v[160:163], v[176:179], v[100:103]
	v_mfma_f32_16x16x32_bf16 v[88:91], v[152:155], v[184:187], v[88:91]
	v_mfma_f32_16x16x32_bf16 v[84:87], v[160:163], v[184:187], v[84:87]
	v_mfma_f32_16x16x32_bf16 v[72:75], v[152:155], v[192:195], v[72:75]
	v_mfma_f32_16x16x32_bf16 v[68:71], v[160:163], v[192:195], v[68:71]
	v_mfma_f32_16x16x32_bf16 v[124:127], v[156:159], v[172:175], v[124:127]
	v_mfma_f32_16x16x32_bf16 v[120:123], v[164:167], v[172:175], v[120:123]
	v_mfma_f32_16x16x32_bf16 v[104:107], v[156:159], v[180:183], v[104:107]
	v_mfma_f32_16x16x32_bf16 v[100:103], v[164:167], v[180:183], v[100:103]
	v_mfma_f32_16x16x32_bf16 v[88:91], v[156:159], v[188:191], v[88:91]
	v_mfma_f32_16x16x32_bf16 v[84:87], v[164:167], v[188:191], v[84:87]
	v_mfma_f32_16x16x32_bf16 v[72:75], v[156:159], v[196:199], v[72:75]
	v_mfma_f32_16x16x32_bf16 v[68:71], v[164:167], v[196:199], v[68:71]
	s_barrier
	s_mov_b32 m0, s19
	ds_read_b128 v[168:171], v239 offset:49152
	ds_read_b128 v[172:175], v239 offset:50176
	ds_read_b128 v[176:179], v239 offset:51200
	ds_read_b128 v[180:183], v239 offset:52224
	ds_read_b128 v[184:187], v239 offset:53248
	ds_read_b128 v[188:191], v239 offset:54272
	ds_read_b128 v[192:195], v239 offset:55296
	ds_read_b128 v[196:199], v239 offset:56320
	buffer_load_dwordx4 v228, s[40:43], s69 offen lds
	s_mov_b32 m0, s25
	s_add_i32 s68, s68, 0x40080
	buffer_load_dwordx4 v230, s[40:43], s69 offen lds
	s_mov_b32 m0, s34
	s_nop 0
	buffer_load_dwordx4 v228, s[40:43], s68 offen lds
	s_mov_b32 m0, s49
	s_nop 0
	buffer_load_dwordx4 v230, s[40:43], s68 offen lds
	s_mov_b32 m0, s27
	s_nop 0
	buffer_load_dwordx4 v115, s[84:87], s67 offen lds
	s_mov_b32 m0, s29
	s_nop 0
	buffer_load_dwordx4 v229, s[84:87], s67 offen lds
	s_waitcnt vmcnt(8)
	s_waitcnt lgkmcnt(0)
	s_barrier
	s_waitcnt lgkmcnt(7)
	v_mfma_f32_16x16x32_bf16 v[64:67], v[128:131], v[168:171], v[64:67]
	v_mfma_f32_16x16x32_bf16 v[60:63], v[144:147], v[168:171], v[60:63]
	s_waitcnt lgkmcnt(5)
	v_mfma_f32_16x16x32_bf16 v[48:51], v[128:131], v[176:179], v[48:51]
	v_mfma_f32_16x16x32_bf16 v[44:47], v[144:147], v[176:179], v[44:47]
	s_waitcnt lgkmcnt(3)
	v_mfma_f32_16x16x32_bf16 v[32:35], v[128:131], v[184:187], v[32:35]
	v_mfma_f32_16x16x32_bf16 v[28:31], v[144:147], v[184:187], v[28:31]
	s_waitcnt lgkmcnt(1)
	v_mfma_f32_16x16x32_bf16 v[16:19], v[128:131], v[192:195], v[16:19]
	v_mfma_f32_16x16x32_bf16 v[12:15], v[144:147], v[192:195], v[12:15]
	v_mfma_f32_16x16x32_bf16 v[64:67], v[140:143], v[172:175], v[64:67]
	v_mfma_f32_16x16x32_bf16 v[60:63], v[148:151], v[172:175], v[60:63]
	v_mfma_f32_16x16x32_bf16 v[48:51], v[140:143], v[180:183], v[48:51]
	v_mfma_f32_16x16x32_bf16 v[44:47], v[148:151], v[180:183], v[44:47]
	v_mfma_f32_16x16x32_bf16 v[32:35], v[140:143], v[188:191], v[32:35]
	v_mfma_f32_16x16x32_bf16 v[28:31], v[148:151], v[188:191], v[28:31]
	s_waitcnt lgkmcnt(0)
	v_mfma_f32_16x16x32_bf16 v[16:19], v[140:143], v[196:199], v[16:19]
	v_mfma_f32_16x16x32_bf16 v[12:15], v[148:151], v[196:199], v[12:15]
	v_mfma_f32_16x16x32_bf16 v[56:59], v[152:155], v[168:171], v[56:59]
	v_mfma_f32_16x16x32_bf16 v[52:55], v[160:163], v[168:171], v[52:55]
	v_mfma_f32_16x16x32_bf16 v[40:43], v[152:155], v[176:179], v[40:43]
	v_mfma_f32_16x16x32_bf16 v[36:39], v[160:163], v[176:179], v[36:39]
	v_mfma_f32_16x16x32_bf16 v[24:27], v[152:155], v[184:187], v[24:27]
	v_mfma_f32_16x16x32_bf16 v[20:23], v[160:163], v[184:187], v[20:23]
	v_mfma_f32_16x16x32_bf16 v[6:9], v[152:155], v[192:195], v[8:11]
	v_mfma_f32_16x16x32_bf16 v[2:5], v[160:163], v[192:195], v[2:5]
	v_mfma_f32_16x16x32_bf16 v[56:59], v[156:159], v[172:175], v[56:59]
	v_mfma_f32_16x16x32_bf16 v[52:55], v[164:167], v[172:175], v[52:55]
	v_mfma_f32_16x16x32_bf16 v[40:43], v[156:159], v[180:183], v[40:43]
	v_mfma_f32_16x16x32_bf16 v[36:39], v[164:167], v[180:183], v[36:39]
	v_mfma_f32_16x16x32_bf16 v[24:27], v[156:159], v[188:191], v[24:27]
	v_mfma_f32_16x16x32_bf16 v[20:23], v[164:167], v[188:191], v[20:23]
	v_mfma_f32_16x16x32_bf16 v[8:11], v[156:159], v[196:199], v[6:9]
	v_mfma_f32_16x16x32_bf16 v[4:7], v[164:167], v[196:199], v[2:5]
	s_barrier
	s_add_i32 s65, s65, 2
	s_addk_i32 s66, 0x100
	s_cmp_gt_u32 s65, 61
	s_cbranch_scc1 .LBB0_55

; #define PG8_BAR __builtin_amdgcn_s_barrier()
; template <class Epi, class Sched, bool ALIGN_EPI, bool SP2>
; __device__ __forceinline__ void gemm_phase(LAS unsigned char* lds, const Gemm g, const Sched& S, const Epi& E, int tid_in) {
;     ...
;         if constexpr (ALIGN_EPI) { if (wr == 0) PG8_BAR; }
;         if constexpr (!Epi::AFTER_DRAIN) { E(acc, cur, wr, wc, fr, fq); }
.LBB0_55:
	s_setprio 0
	v_mov_b32_e32 v243, 0x3e4ccccd
	v_mov_b32_e32 v242, 0x358637bd
	s_and_b64 vcc, exec, s[46:47]
	s_cbranch_vccz .LBB0_57
	s_barrier
